# hyena conv loop rewritten (rolling B window), in-proj LDS-DMA 2-stage, outproj9 epilogue pipelined, prep item rebalance
# speedup vs baseline: 1.0422x; 1.0422x over previous
.LBB0_558:
	v_add_u32_e32 v245, 0x8000, v233
	ds_read_b128 v[70:73], v245
	ds_read_b128 v[74:77], v245
	ds_read_b128 v[78:81], v245
	ds_read_b128 v[82:85], v245
	ds_read_b128 v[86:89], v245
	ds_read_b128 v[90:93], v245
	ds_read_b128 v[94:97], v245
	ds_read2_b64 v[98:101], v232 offset1:1
	ds_read2_b64 v[102:105], v231 offset1:1
	v_and_b32_e32 v244, 8, v189
	v_add_u32_e32 v244, 63, v244
	v_min_u32_e32 v246, 64, v244
	v_lshl_or_b32 v246, v246, 9, v233
	ds_read_b128 v[66:69], v246
	v_add_u32_e32 v247, 0xfffffe00, v231
	v_mov_b32_e32 v2, 0
	v_mov_b32_e32 v3, 0
	v_mov_b32_e32 v4, 0
	v_mov_b32_e32 v5, 0
	v_mov_b32_e32 v6, 0
	v_mov_b32_e32 v7, 0
	v_mov_b32_e32 v8, 0
	v_mov_b32_e32 v9, 0
	v_mov_b32_e32 v10, 0
	v_mov_b32_e32 v11, 0
	v_mov_b32_e32 v12, 0
	v_mov_b32_e32 v13, 0
	v_mov_b32_e32 v14, 0
	v_mov_b32_e32 v15, 0
	v_mov_b32_e32 v16, 0
	v_mov_b32_e32 v17, 0
	v_mov_b32_e32 v18, 0
	v_mov_b32_e32 v19, 0
	v_mov_b32_e32 v20, 0
	v_mov_b32_e32 v21, 0
	v_mov_b32_e32 v22, 0
	v_mov_b32_e32 v23, 0
	v_mov_b32_e32 v24, 0
	v_mov_b32_e32 v25, 0
	v_mov_b32_e32 v26, 0
	v_mov_b32_e32 v27, 0
	v_mov_b32_e32 v28, 0
	v_mov_b32_e32 v29, 0
	v_mov_b32_e32 v30, 0
	v_mov_b32_e32 v31, 0
	v_mov_b32_e32 v32, 0
	v_mov_b32_e32 v33, 0
	v_mov_b32_e32 v34, 0
	v_mov_b32_e32 v35, 0
	v_mov_b32_e32 v36, 0
	v_mov_b32_e32 v37, 0
	v_mov_b32_e32 v38, 0
	v_mov_b32_e32 v39, 0
	v_mov_b32_e32 v40, 0
	v_mov_b32_e32 v41, 0
	v_mov_b32_e32 v42, 0
	v_mov_b32_e32 v43, 0
	v_mov_b32_e32 v44, 0
	v_mov_b32_e32 v45, 0
	v_mov_b32_e32 v46, 0
	v_mov_b32_e32 v47, 0
	v_mov_b32_e32 v48, 0
	v_mov_b32_e32 v49, 0
	v_mov_b32_e32 v50, 0
	v_mov_b32_e32 v51, 0
	v_mov_b32_e32 v52, 0
	v_mov_b32_e32 v53, 0
	v_mov_b32_e32 v54, 0
	v_mov_b32_e32 v55, 0
	v_mov_b32_e32 v56, 0
	v_mov_b32_e32 v57, 0
	v_mov_b32_e32 v58, 0
	v_mov_b32_e32 v59, 0
	v_mov_b32_e32 v60, 0
	v_mov_b32_e32 v61, 0
	v_mov_b32_e32 v62, 0
	v_mov_b32_e32 v63, 0
	v_mov_b32_e32 v64, 0
	v_mov_b32_e32 v65, 0
	s_mov_b32 s68, 0
.Lhy8_loop:
	ds_read2_b64 v[108:111], v247 offset0:60 offset1:61
	ds_read2_b64 v[202:205], v247 offset0:56 offset1:57
	v_add_u32_e32 v244, -1, v244
	v_min_u32_e32 v245, 64, v244
	v_lshl_or_b32 v245, v245, 9, v233
	s_waitcnt lgkmcnt(3)
	v_mfma_f32_16x16x32_bf16 v[58:61], v[98:101], v[70:73], v[58:61]
	v_mfma_f32_16x16x32_bf16 v[62:65], v[102:105], v[70:73], v[62:65]
	ds_read_b128 v[70:73], v245
	v_mfma_f32_16x16x32_bf16 v[50:53], v[98:101], v[74:77], v[50:53]
	v_mfma_f32_16x16x32_bf16 v[54:57], v[102:105], v[74:77], v[54:57]
	v_mfma_f32_16x16x32_bf16 v[42:45], v[98:101], v[78:81], v[42:45]
	v_mfma_f32_16x16x32_bf16 v[46:49], v[102:105], v[78:81], v[46:49]
	v_mfma_f32_16x16x32_bf16 v[34:37], v[98:101], v[82:85], v[34:37]
	v_mfma_f32_16x16x32_bf16 v[38:41], v[102:105], v[82:85], v[38:41]
	v_mfma_f32_16x16x32_bf16 v[26:29], v[98:101], v[86:89], v[26:29]
	v_mfma_f32_16x16x32_bf16 v[30:33], v[102:105], v[86:89], v[30:33]
	v_mfma_f32_16x16x32_bf16 v[18:21], v[98:101], v[90:93], v[18:21]
	v_mfma_f32_16x16x32_bf16 v[22:25], v[102:105], v[90:93], v[22:25]
	v_mfma_f32_16x16x32_bf16 v[10:13], v[98:101], v[94:97], v[10:13]
	v_mfma_f32_16x16x32_bf16 v[14:17], v[102:105], v[94:97], v[14:17]
	s_waitcnt lgkmcnt(3)
	v_mfma_f32_16x16x32_bf16 v[2:5], v[98:101], v[66:69], v[2:5]
	v_mfma_f32_16x16x32_bf16 v[6:9], v[102:105], v[66:69], v[6:9]
	ds_read2_b64 v[98:101], v247 offset0:52 offset1:53
	ds_read2_b64 v[102:105], v247 offset0:48 offset1:49
	v_add_u32_e32 v244, -1, v244
	v_min_u32_e32 v245, 64, v244
	v_lshl_or_b32 v245, v245, 9, v233
	s_waitcnt lgkmcnt(3)
	v_mfma_f32_16x16x32_bf16 v[58:61], v[108:111], v[74:77], v[58:61]
	v_mfma_f32_16x16x32_bf16 v[62:65], v[202:205], v[74:77], v[62:65]
	ds_read_b128 v[74:77], v245
	v_mfma_f32_16x16x32_bf16 v[50:53], v[108:111], v[78:81], v[50:53]
	v_mfma_f32_16x16x32_bf16 v[54:57], v[202:205], v[78:81], v[54:57]
	v_mfma_f32_16x16x32_bf16 v[42:45], v[108:111], v[82:85], v[42:45]
	v_mfma_f32_16x16x32_bf16 v[46:49], v[202:205], v[82:85], v[46:49]
	v_mfma_f32_16x16x32_bf16 v[34:37], v[108:111], v[86:89], v[34:37]
	v_mfma_f32_16x16x32_bf16 v[38:41], v[202:205], v[86:89], v[38:41]
	v_mfma_f32_16x16x32_bf16 v[26:29], v[108:111], v[90:93], v[26:29]
	v_mfma_f32_16x16x32_bf16 v[30:33], v[202:205], v[90:93], v[30:33]
	v_mfma_f32_16x16x32_bf16 v[18:21], v[108:111], v[94:97], v[18:21]
	v_mfma_f32_16x16x32_bf16 v[22:25], v[202:205], v[94:97], v[22:25]
	v_mfma_f32_16x16x32_bf16 v[10:13], v[108:111], v[66:69], v[10:13]
	v_mfma_f32_16x16x32_bf16 v[14:17], v[202:205], v[66:69], v[14:17]
	s_waitcnt lgkmcnt(3)
	v_mfma_f32_16x16x32_bf16 v[2:5], v[108:111], v[70:73], v[2:5]
	v_mfma_f32_16x16x32_bf16 v[6:9], v[202:205], v[70:73], v[6:9]
	ds_read2_b64 v[108:111], v247 offset0:44 offset1:45
	ds_read2_b64 v[202:205], v247 offset0:40 offset1:41
	v_add_u32_e32 v244, -1, v244
	v_min_u32_e32 v245, 64, v244
	v_lshl_or_b32 v245, v245, 9, v233
	s_waitcnt lgkmcnt(3)
	v_mfma_f32_16x16x32_bf16 v[58:61], v[98:101], v[78:81], v[58:61]
	v_mfma_f32_16x16x32_bf16 v[62:65], v[102:105], v[78:81], v[62:65]
	ds_read_b128 v[78:81], v245
	v_mfma_f32_16x16x32_bf16 v[50:53], v[98:101], v[82:85], v[50:53]
	v_mfma_f32_16x16x32_bf16 v[54:57], v[102:105], v[82:85], v[54:57]
	v_mfma_f32_16x16x32_bf16 v[42:45], v[98:101], v[86:89], v[42:45]
	v_mfma_f32_16x16x32_bf16 v[46:49], v[102:105], v[86:89], v[46:49]
	v_mfma_f32_16x16x32_bf16 v[34:37], v[98:101], v[90:93], v[34:37]
	v_mfma_f32_16x16x32_bf16 v[38:41], v[102:105], v[90:93], v[38:41]
	v_mfma_f32_16x16x32_bf16 v[26:29], v[98:101], v[94:97], v[26:29]
	v_mfma_f32_16x16x32_bf16 v[30:33], v[102:105], v[94:97], v[30:33]
	v_mfma_f32_16x16x32_bf16 v[18:21], v[98:101], v[66:69], v[18:21]
	v_mfma_f32_16x16x32_bf16 v[22:25], v[102:105], v[66:69], v[22:25]
	v_mfma_f32_16x16x32_bf16 v[10:13], v[98:101], v[70:73], v[10:13]
	v_mfma_f32_16x16x32_bf16 v[14:17], v[102:105], v[70:73], v[14:17]
	s_waitcnt lgkmcnt(3)
	v_mfma_f32_16x16x32_bf16 v[2:5], v[98:101], v[74:77], v[2:5]
	v_mfma_f32_16x16x32_bf16 v[6:9], v[102:105], v[74:77], v[6:9]
	ds_read2_b64 v[98:101], v247 offset0:36 offset1:37
	ds_read2_b64 v[102:105], v247 offset0:32 offset1:33
	v_add_u32_e32 v244, -1, v244
	v_min_u32_e32 v245, 64, v244
	v_lshl_or_b32 v245, v245, 9, v233
	s_waitcnt lgkmcnt(3)
	v_mfma_f32_16x16x32_bf16 v[58:61], v[108:111], v[82:85], v[58:61]
	v_mfma_f32_16x16x32_bf16 v[62:65], v[202:205], v[82:85], v[62:65]
	ds_read_b128 v[82:85], v245
	v_mfma_f32_16x16x32_bf16 v[50:53], v[108:111], v[86:89], v[50:53]
	v_mfma_f32_16x16x32_bf16 v[54:57], v[202:205], v[86:89], v[54:57]
	v_mfma_f32_16x16x32_bf16 v[42:45], v[108:111], v[90:93], v[42:45]
	v_mfma_f32_16x16x32_bf16 v[46:49], v[202:205], v[90:93], v[46:49]
	v_mfma_f32_16x16x32_bf16 v[34:37], v[108:111], v[94:97], v[34:37]
	v_mfma_f32_16x16x32_bf16 v[38:41], v[202:205], v[94:97], v[38:41]
	v_mfma_f32_16x16x32_bf16 v[26:29], v[108:111], v[66:69], v[26:29]
	v_mfma_f32_16x16x32_bf16 v[30:33], v[202:205], v[66:69], v[30:33]
	v_mfma_f32_16x16x32_bf16 v[18:21], v[108:111], v[70:73], v[18:21]
	v_mfma_f32_16x16x32_bf16 v[22:25], v[202:205], v[70:73], v[22:25]
	v_mfma_f32_16x16x32_bf16 v[10:13], v[108:111], v[74:77], v[10:13]
	v_mfma_f32_16x16x32_bf16 v[14:17], v[202:205], v[74:77], v[14:17]
	s_waitcnt lgkmcnt(3)
	v_mfma_f32_16x16x32_bf16 v[2:5], v[108:111], v[78:81], v[2:5]
	v_mfma_f32_16x16x32_bf16 v[6:9], v[202:205], v[78:81], v[6:9]
	ds_read2_b64 v[108:111], v247 offset0:28 offset1:29
	ds_read2_b64 v[202:205], v247 offset0:24 offset1:25
	v_add_u32_e32 v244, -1, v244
	v_min_u32_e32 v245, 64, v244
	v_lshl_or_b32 v245, v245, 9, v233
	s_waitcnt lgkmcnt(3)
	v_mfma_f32_16x16x32_bf16 v[58:61], v[98:101], v[86:89], v[58:61]
	v_mfma_f32_16x16x32_bf16 v[62:65], v[102:105], v[86:89], v[62:65]
	ds_read_b128 v[86:89], v245
	v_mfma_f32_16x16x32_bf16 v[50:53], v[98:101], v[90:93], v[50:53]
	v_mfma_f32_16x16x32_bf16 v[54:57], v[102:105], v[90:93], v[54:57]
	v_mfma_f32_16x16x32_bf16 v[42:45], v[98:101], v[94:97], v[42:45]
	v_mfma_f32_16x16x32_bf16 v[46:49], v[102:105], v[94:97], v[46:49]
	v_mfma_f32_16x16x32_bf16 v[34:37], v[98:101], v[66:69], v[34:37]
	v_mfma_f32_16x16x32_bf16 v[38:41], v[102:105], v[66:69], v[38:41]
	v_mfma_f32_16x16x32_bf16 v[26:29], v[98:101], v[70:73], v[26:29]
	v_mfma_f32_16x16x32_bf16 v[30:33], v[102:105], v[70:73], v[30:33]
	v_mfma_f32_16x16x32_bf16 v[18:21], v[98:101], v[74:77], v[18:21]
	v_mfma_f32_16x16x32_bf16 v[22:25], v[102:105], v[74:77], v[22:25]
	v_mfma_f32_16x16x32_bf16 v[10:13], v[98:101], v[78:81], v[10:13]
	v_mfma_f32_16x16x32_bf16 v[14:17], v[102:105], v[78:81], v[14:17]
	s_waitcnt lgkmcnt(3)
	v_mfma_f32_16x16x32_bf16 v[2:5], v[98:101], v[82:85], v[2:5]
	v_mfma_f32_16x16x32_bf16 v[6:9], v[102:105], v[82:85], v[6:9]
	ds_read2_b64 v[98:101], v247 offset0:20 offset1:21
	ds_read2_b64 v[102:105], v247 offset0:16 offset1:17
	v_add_u32_e32 v244, -1, v244
	v_min_u32_e32 v245, 64, v244
	v_lshl_or_b32 v245, v245, 9, v233
	s_waitcnt lgkmcnt(3)
	v_mfma_f32_16x16x32_bf16 v[58:61], v[108:111], v[90:93], v[58:61]
	v_mfma_f32_16x16x32_bf16 v[62:65], v[202:205], v[90:93], v[62:65]
	ds_read_b128 v[90:93], v245
	v_mfma_f32_16x16x32_bf16 v[50:53], v[108:111], v[94:97], v[50:53]
	v_mfma_f32_16x16x32_bf16 v[54:57], v[202:205], v[94:97], v[54:57]
	v_mfma_f32_16x16x32_bf16 v[42:45], v[108:111], v[66:69], v[42:45]
	v_mfma_f32_16x16x32_bf16 v[46:49], v[202:205], v[66:69], v[46:49]
	v_mfma_f32_16x16x32_bf16 v[34:37], v[108:111], v[70:73], v[34:37]
	v_mfma_f32_16x16x32_bf16 v[38:41], v[202:205], v[70:73], v[38:41]
	v_mfma_f32_16x16x32_bf16 v[26:29], v[108:111], v[74:77], v[26:29]
	v_mfma_f32_16x16x32_bf16 v[30:33], v[202:205], v[74:77], v[30:33]
	v_mfma_f32_16x16x32_bf16 v[18:21], v[108:111], v[78:81], v[18:21]
	v_mfma_f32_16x16x32_bf16 v[22:25], v[202:205], v[78:81], v[22:25]
	v_mfma_f32_16x16x32_bf16 v[10:13], v[108:111], v[82:85], v[10:13]
	v_mfma_f32_16x16x32_bf16 v[14:17], v[202:205], v[82:85], v[14:17]
	s_waitcnt lgkmcnt(3)
	v_mfma_f32_16x16x32_bf16 v[2:5], v[108:111], v[86:89], v[2:5]
	v_mfma_f32_16x16x32_bf16 v[6:9], v[202:205], v[86:89], v[6:9]
	ds_read2_b64 v[108:111], v247 offset0:12 offset1:13
	ds_read2_b64 v[202:205], v247 offset0:8 offset1:9
	v_add_u32_e32 v244, -1, v244
	v_min_u32_e32 v245, 64, v244
	v_lshl_or_b32 v245, v245, 9, v233
	s_waitcnt lgkmcnt(3)
	v_mfma_f32_16x16x32_bf16 v[58:61], v[98:101], v[94:97], v[58:61]
	v_mfma_f32_16x16x32_bf16 v[62:65], v[102:105], v[94:97], v[62:65]
	ds_read_b128 v[94:97], v245
	v_mfma_f32_16x16x32_bf16 v[50:53], v[98:101], v[66:69], v[50:53]
	v_mfma_f32_16x16x32_bf16 v[54:57], v[102:105], v[66:69], v[54:57]
	v_mfma_f32_16x16x32_bf16 v[42:45], v[98:101], v[70:73], v[42:45]
	v_mfma_f32_16x16x32_bf16 v[46:49], v[102:105], v[70:73], v[46:49]
	v_mfma_f32_16x16x32_bf16 v[34:37], v[98:101], v[74:77], v[34:37]
	v_mfma_f32_16x16x32_bf16 v[38:41], v[102:105], v[74:77], v[38:41]
	v_mfma_f32_16x16x32_bf16 v[26:29], v[98:101], v[78:81], v[26:29]
	v_mfma_f32_16x16x32_bf16 v[30:33], v[102:105], v[78:81], v[30:33]
	v_mfma_f32_16x16x32_bf16 v[18:21], v[98:101], v[82:85], v[18:21]
	v_mfma_f32_16x16x32_bf16 v[22:25], v[102:105], v[82:85], v[22:25]
	v_mfma_f32_16x16x32_bf16 v[10:13], v[98:101], v[86:89], v[10:13]
	v_mfma_f32_16x16x32_bf16 v[14:17], v[102:105], v[86:89], v[14:17]
	s_waitcnt lgkmcnt(3)
	v_mfma_f32_16x16x32_bf16 v[2:5], v[98:101], v[90:93], v[2:5]
	v_mfma_f32_16x16x32_bf16 v[6:9], v[102:105], v[90:93], v[6:9]
	s_cmp_eq_u32 s68, 9
	s_cbranch_scc1 .Lhy8_done
	ds_read2_b64 v[98:101], v247 offset0:4 offset1:5
	ds_read2_b64 v[102:105], v247 offset0:0 offset1:1
	v_add_u32_e32 v244, -1, v244
	v_min_u32_e32 v245, 64, v244
	v_lshl_or_b32 v245, v245, 9, v233
	s_waitcnt lgkmcnt(3)
	v_mfma_f32_16x16x32_bf16 v[58:61], v[108:111], v[66:69], v[58:61]
	v_mfma_f32_16x16x32_bf16 v[62:65], v[202:205], v[66:69], v[62:65]
	ds_read_b128 v[66:69], v245
	v_mfma_f32_16x16x32_bf16 v[50:53], v[108:111], v[70:73], v[50:53]
	v_mfma_f32_16x16x32_bf16 v[54:57], v[202:205], v[70:73], v[54:57]
	v_mfma_f32_16x16x32_bf16 v[42:45], v[108:111], v[74:77], v[42:45]
	v_mfma_f32_16x16x32_bf16 v[46:49], v[202:205], v[74:77], v[46:49]
	v_mfma_f32_16x16x32_bf16 v[34:37], v[108:111], v[78:81], v[34:37]
	v_mfma_f32_16x16x32_bf16 v[38:41], v[202:205], v[78:81], v[38:41]
	v_mfma_f32_16x16x32_bf16 v[26:29], v[108:111], v[82:85], v[26:29]
	v_mfma_f32_16x16x32_bf16 v[30:33], v[202:205], v[82:85], v[30:33]
	v_mfma_f32_16x16x32_bf16 v[18:21], v[108:111], v[86:89], v[18:21]
	v_mfma_f32_16x16x32_bf16 v[22:25], v[202:205], v[86:89], v[22:25]
	v_mfma_f32_16x16x32_bf16 v[10:13], v[108:111], v[90:93], v[10:13]
	v_mfma_f32_16x16x32_bf16 v[14:17], v[202:205], v[90:93], v[14:17]
	s_waitcnt lgkmcnt(3)
	v_mfma_f32_16x16x32_bf16 v[2:5], v[108:111], v[94:97], v[2:5]
	v_mfma_f32_16x16x32_bf16 v[6:9], v[202:205], v[94:97], v[6:9]
	s_add_i32 s68, s68, 1
	v_add_u32_e32 v247, 0xfffffe00, v247
	s_branch .Lhy8_loop
.Lhy8_done:
	s_add_i32 s68, s29, s76
	s_ashr_i32 s69, s68, 31
	s_lshl_b64 s[68:69], s[68:69], 2
	s_add_u32 s68, s44, s68
	s_addc_u32 s69, s45, s69
	s_add_i32 s71, s1, 63
	s_lshl_b32 s71, s71, 9
	s_waitcnt lgkmcnt(0)
	s_barrier
	global_load_dword v0, v1, s[68:69]
	v_and_b32_e32 v234, 8, v189
	v_lshlrev_b32_e32 v234, 9, v234
	v_and_b32_e32 v235, 2, v190
	v_lshl_or_b32 v234, v235, 6, v234
	v_and_b32_e32 v235, 7, v189
	v_lshl_or_b32 v234, v235, 4, v234
	v_and_b32_e32 v235, 1, v190
	v_lshl_or_b32 v234, v235, 3, v234
	v_add_u32_e32 v234, s71, v234
	s_and_b64 s[20:21], exec, s[20:21]
	s_cselect_b32 s20, s0, s28
	s_cselect_b32 s70, s58, s59
	s_ashr_i32 s21, s20, 31
	s_lshl_b64 s[20:21], s[20:21], 2
	v_readlane_b32 s68, v252, 60
	s_add_u32 s68, s68, s20
	v_readlane_b32 s69, v252, 61
	s_addc_u32 s69, s69, s21
	ds_read_b64 v[66:67], v234 offset:0
	ds_read_b64 v[68:69], v234 offset:256
	ds_read_b64 v[70:71], v234 offset:512
	ds_read_b64 v[72:73], v234 offset:768
	ds_read_b64 v[74:75], v234 offset:1024
	ds_read_b64 v[76:77], v234 offset:1280
	ds_read_b64 v[78:79], v234 offset:1536
	ds_read_b64 v[80:81], v234 offset:1792
	s_waitcnt vmcnt(0)
	s_waitcnt lgkmcnt(7)
	v_lshlrev_b32_e32 v82, 16, v66
	v_and_b32_e32 v83, 0xffff0000, v66
	v_lshlrev_b32_e32 v84, 16, v67
	v_and_b32_e32 v85, 0xffff0000, v67
	v_pk_fma_f32 v[2:3], v[0:1], v[82:83], v[2:3] op_sel_hi:[0,1,1]
	v_pk_fma_f32 v[4:5], v[0:1], v[84:85], v[4:5] op_sel_hi:[0,1,1]
	v_cvt_pk_bf16_f32 v2, v2, v3
	v_cvt_pk_bf16_f32 v3, v4, v5
	ds_write_b64 v234, v[2:3] offset:0
	s_waitcnt lgkmcnt(7)
	v_lshlrev_b32_e32 v86, 16, v68
	v_and_b32_e32 v87, 0xffff0000, v68
	v_lshlrev_b32_e32 v88, 16, v69
	v_and_b32_e32 v89, 0xffff0000, v69
	v_pk_fma_f32 v[6:7], v[0:1], v[86:87], v[6:7] op_sel_hi:[0,1,1]
	v_pk_fma_f32 v[8:9], v[0:1], v[88:89], v[8:9] op_sel_hi:[0,1,1]
	v_cvt_pk_bf16_f32 v6, v6, v7
	v_cvt_pk_bf16_f32 v7, v8, v9
	ds_write_b64 v234, v[6:7] offset:256
	s_waitcnt lgkmcnt(7)
	v_lshlrev_b32_e32 v90, 16, v70
	v_and_b32_e32 v91, 0xffff0000, v70
	v_lshlrev_b32_e32 v92, 16, v71
	v_and_b32_e32 v93, 0xffff0000, v71
	v_pk_fma_f32 v[10:11], v[0:1], v[90:91], v[10:11] op_sel_hi:[0,1,1]
	v_pk_fma_f32 v[12:13], v[0:1], v[92:93], v[12:13] op_sel_hi:[0,1,1]
	v_cvt_pk_bf16_f32 v10, v10, v11
	v_cvt_pk_bf16_f32 v11, v12, v13
	ds_write_b64 v234, v[10:11] offset:512
	s_waitcnt lgkmcnt(7)
	v_lshlrev_b32_e32 v94, 16, v72
	v_and_b32_e32 v95, 0xffff0000, v72
	v_lshlrev_b32_e32 v96, 16, v73
	v_and_b32_e32 v97, 0xffff0000, v73
	v_pk_fma_f32 v[14:15], v[0:1], v[94:95], v[14:15] op_sel_hi:[0,1,1]
	v_pk_fma_f32 v[16:17], v[0:1], v[96:97], v[16:17] op_sel_hi:[0,1,1]
	v_cvt_pk_bf16_f32 v14, v14, v15
	v_cvt_pk_bf16_f32 v15, v16, v17
	ds_write_b64 v234, v[14:15] offset:768
	s_waitcnt lgkmcnt(7)
	v_lshlrev_b32_e32 v82, 16, v74
	v_and_b32_e32 v83, 0xffff0000, v74
	v_lshlrev_b32_e32 v84, 16, v75
	v_and_b32_e32 v85, 0xffff0000, v75
	v_pk_fma_f32 v[18:19], v[0:1], v[82:83], v[18:19] op_sel_hi:[0,1,1]
	v_pk_fma_f32 v[20:21], v[0:1], v[84:85], v[20:21] op_sel_hi:[0,1,1]
	v_cvt_pk_bf16_f32 v18, v18, v19
	v_cvt_pk_bf16_f32 v19, v20, v21
	ds_write_b64 v234, v[18:19] offset:1024
	s_waitcnt lgkmcnt(7)
	v_lshlrev_b32_e32 v86, 16, v76
	v_and_b32_e32 v87, 0xffff0000, v76
	v_lshlrev_b32_e32 v88, 16, v77
	v_and_b32_e32 v89, 0xffff0000, v77
	v_pk_fma_f32 v[22:23], v[0:1], v[86:87], v[22:23] op_sel_hi:[0,1,1]
	v_pk_fma_f32 v[24:25], v[0:1], v[88:89], v[24:25] op_sel_hi:[0,1,1]
	v_cvt_pk_bf16_f32 v22, v22, v23
	v_cvt_pk_bf16_f32 v23, v24, v25
	ds_write_b64 v234, v[22:23] offset:1280
	s_waitcnt lgkmcnt(7)
	v_lshlrev_b32_e32 v90, 16, v78
	v_and_b32_e32 v91, 0xffff0000, v78
	v_lshlrev_b32_e32 v92, 16, v79
	v_and_b32_e32 v93, 0xffff0000, v79
	v_pk_fma_f32 v[26:27], v[0:1], v[90:91], v[26:27] op_sel_hi:[0,1,1]
	v_pk_fma_f32 v[28:29], v[0:1], v[92:93], v[28:29] op_sel_hi:[0,1,1]
	v_cvt_pk_bf16_f32 v26, v26, v27
	v_cvt_pk_bf16_f32 v27, v28, v29
	ds_write_b64 v234, v[26:27] offset:1536
	s_waitcnt lgkmcnt(7)
	v_lshlrev_b32_e32 v94, 16, v80
	v_and_b32_e32 v95, 0xffff0000, v80
	v_lshlrev_b32_e32 v96, 16, v81
	v_and_b32_e32 v97, 0xffff0000, v81
	v_pk_fma_f32 v[30:31], v[0:1], v[94:95], v[30:31] op_sel_hi:[0,1,1]
	v_pk_fma_f32 v[32:33], v[0:1], v[96:97], v[32:33] op_sel_hi:[0,1,1]
	v_cvt_pk_bf16_f32 v30, v30, v31
	v_cvt_pk_bf16_f32 v31, v32, v33
	ds_write_b64 v234, v[30:31] offset:1792
	ds_read_b64 v[66:67], v234 offset:2048
	ds_read_b64 v[68:69], v234 offset:2304
	ds_read_b64 v[70:71], v234 offset:2560
	ds_read_b64 v[72:73], v234 offset:2816
	ds_read_b64 v[74:75], v234 offset:3072
	ds_read_b64 v[76:77], v234 offset:3328
	ds_read_b64 v[78:79], v234 offset:3584
	ds_read_b64 v[80:81], v234 offset:3840
	s_waitcnt lgkmcnt(7)
	v_lshlrev_b32_e32 v82, 16, v66
	v_and_b32_e32 v83, 0xffff0000, v66
	v_lshlrev_b32_e32 v84, 16, v67
	v_and_b32_e32 v85, 0xffff0000, v67
	v_pk_fma_f32 v[34:35], v[0:1], v[82:83], v[34:35] op_sel_hi:[0,1,1]
	v_pk_fma_f32 v[36:37], v[0:1], v[84:85], v[36:37] op_sel_hi:[0,1,1]
	v_cvt_pk_bf16_f32 v34, v34, v35
	v_cvt_pk_bf16_f32 v35, v36, v37
	ds_write_b64 v234, v[34:35] offset:2048
	s_waitcnt lgkmcnt(7)
	v_lshlrev_b32_e32 v86, 16, v68
	v_and_b32_e32 v87, 0xffff0000, v68
	v_lshlrev_b32_e32 v88, 16, v69
	v_and_b32_e32 v89, 0xffff0000, v69
	v_pk_fma_f32 v[38:39], v[0:1], v[86:87], v[38:39] op_sel_hi:[0,1,1]
	v_pk_fma_f32 v[40:41], v[0:1], v[88:89], v[40:41] op_sel_hi:[0,1,1]
	v_cvt_pk_bf16_f32 v38, v38, v39
	v_cvt_pk_bf16_f32 v39, v40, v41
	ds_write_b64 v234, v[38:39] offset:2304
	s_waitcnt lgkmcnt(7)
	v_lshlrev_b32_e32 v90, 16, v70
	v_and_b32_e32 v91, 0xffff0000, v70
	v_lshlrev_b32_e32 v92, 16, v71
	v_and_b32_e32 v93, 0xffff0000, v71
	v_pk_fma_f32 v[42:43], v[0:1], v[90:91], v[42:43] op_sel_hi:[0,1,1]
	v_pk_fma_f32 v[44:45], v[0:1], v[92:93], v[44:45] op_sel_hi:[0,1,1]
	v_cvt_pk_bf16_f32 v42, v42, v43
	v_cvt_pk_bf16_f32 v43, v44, v45
	ds_write_b64 v234, v[42:43] offset:2560
	s_waitcnt lgkmcnt(7)
	v_lshlrev_b32_e32 v94, 16, v72
	v_and_b32_e32 v95, 0xffff0000, v72
	v_lshlrev_b32_e32 v96, 16, v73
	v_and_b32_e32 v97, 0xffff0000, v73
	v_pk_fma_f32 v[46:47], v[0:1], v[94:95], v[46:47] op_sel_hi:[0,1,1]
	v_pk_fma_f32 v[48:49], v[0:1], v[96:97], v[48:49] op_sel_hi:[0,1,1]
	v_cvt_pk_bf16_f32 v46, v46, v47
	v_cvt_pk_bf16_f32 v47, v48, v49
	ds_write_b64 v234, v[46:47] offset:2816
	s_waitcnt lgkmcnt(7)
	v_lshlrev_b32_e32 v82, 16, v74
	v_and_b32_e32 v83, 0xffff0000, v74
	v_lshlrev_b32_e32 v84, 16, v75
	v_and_b32_e32 v85, 0xffff0000, v75
	v_pk_fma_f32 v[50:51], v[0:1], v[82:83], v[50:51] op_sel_hi:[0,1,1]
	v_pk_fma_f32 v[52:53], v[0:1], v[84:85], v[52:53] op_sel_hi:[0,1,1]
	v_cvt_pk_bf16_f32 v50, v50, v51
	v_cvt_pk_bf16_f32 v51, v52, v53
	ds_write_b64 v234, v[50:51] offset:3072
	s_waitcnt lgkmcnt(7)
	v_lshlrev_b32_e32 v86, 16, v76
	v_and_b32_e32 v87, 0xffff0000, v76
	v_lshlrev_b32_e32 v88, 16, v77
	v_and_b32_e32 v89, 0xffff0000, v77
	v_pk_fma_f32 v[54:55], v[0:1], v[86:87], v[54:55] op_sel_hi:[0,1,1]
	v_pk_fma_f32 v[56:57], v[0:1], v[88:89], v[56:57] op_sel_hi:[0,1,1]
	v_cvt_pk_bf16_f32 v54, v54, v55
	v_cvt_pk_bf16_f32 v55, v56, v57
	ds_write_b64 v234, v[54:55] offset:3328
	s_waitcnt lgkmcnt(7)
	v_lshlrev_b32_e32 v90, 16, v78
	v_and_b32_e32 v91, 0xffff0000, v78
	v_lshlrev_b32_e32 v92, 16, v79
	v_and_b32_e32 v93, 0xffff0000, v79
	v_pk_fma_f32 v[58:59], v[0:1], v[90:91], v[58:59] op_sel_hi:[0,1,1]
	v_pk_fma_f32 v[60:61], v[0:1], v[92:93], v[60:61] op_sel_hi:[0,1,1]
	v_cvt_pk_bf16_f32 v58, v58, v59
	v_cvt_pk_bf16_f32 v59, v60, v61
	ds_write_b64 v234, v[58:59] offset:3584
	s_waitcnt lgkmcnt(7)
	v_lshlrev_b32_e32 v94, 16, v80
	v_and_b32_e32 v95, 0xffff0000, v80
	v_lshlrev_b32_e32 v96, 16, v81
	v_and_b32_e32 v97, 0xffff0000, v81
	v_pk_fma_f32 v[62:63], v[0:1], v[94:95], v[62:63] op_sel_hi:[0,1,1]
	v_pk_fma_f32 v[64:65], v[0:1], v[96:97], v[64:65] op_sel_hi:[0,1,1]
	v_cvt_pk_bf16_f32 v62, v62, v63
	v_cvt_pk_bf16_f32 v63, v64, v65
	ds_write_b64 v234, v[62:63] offset:3840
	s_waitcnt lgkmcnt(0)
	s_barrier
	global_load_dword v34, v1, s[68:69]
	global_load_dword v36, v1, s[68:69] offset:3072
	global_load_dword v38, v243, s[68:69] offset:2048
	v_readlane_b32 s68, v252, 62
	s_add_u32 s20, s68, s20
	v_readlane_b32 s68, v252, 63
	s_addc_u32 s21, s68, s21
	global_load_dword v40, v1, s[20:21]
	s_mul_hi_i32 s20, s70, 0x9000
	s_mul_i32 s70, s70, 0x9000
	v_readlane_b32 s68, v250, 10
	v_readlane_b32 s69, v250, 11
	s_add_u32 s68, s68, s70
	s_addc_u32 s69, s69, s20
	s_mov_b32 s20, 0
	s_mov_b64 s[70:71], -1
	s_waitcnt vmcnt(3)
	v_mov_b32_e32 v35, v34
	s_waitcnt vmcnt(2)
	v_mov_b32_e32 v37, v36
	s_waitcnt vmcnt(1)
	v_mov_b32_e32 v39, v38
	v_mov_b32_e32 v42, v36
	v_mov_b32_e32 v43, v34
	s_waitcnt vmcnt(0)
	v_mov_b32_e32 v41, v40
	s_branch .LBB0_564

.LBB0_714:
	s_lshr_b32 s5, s11, 3
	s_and_b32 s5, s5, 7
	s_lshl_b32 s15, s5, 7
	s_lshl_b32 s5, s11, 3
	s_and_b32 s5, s5, 56
	s_bfe_u32 s17, s11, 0x30006
	s_bfe_u32 s16, s10, 0x30003
	s_or_b32 s12, s5, s17
	s_mulk_i32 s16, 0x900
	s_mulk_i32 s17, 0x120
	s_mulk_i32 s12, 0x120
	s_andn2_b64 vcc, exec, s[0:1]
	s_mov_b64 s[0:1], -1
	s_cbranch_vccz .LBB0_731
	v_readfirstlane_b32 s13, v175
	v_lshrrev_b32_e32 v55, 3, v175
	v_and_b32_e32 v55, 6, v55
	s_movk_i32 s16, 0x78
	v_lshrrev_b32_e64 v55, v55, s16
	v_xor_b32_e32 v55, v55, v175
	v_and_b32_e32 v55, 3, v55
	v_lshlrev_b32_e32 v55, 4, v55
	v_lshrrev_b32_e32 v56, 2, v175
	v_lshl_or_b32 v50, v56, 11, v55
	v_add_u32_e32 v51, 0x20000, v50
	v_add_u32_e32 v52, 0x40000, v50
	v_add_u32_e32 v53, 0x60000, v50
	v_add_u32_e32 v54, 0x80000, v50
	s_lshl_b32 s16, s12, 11
	s_add_u32 s6, s96, s16
	s_addc_u32 s7, s97, 0
	v_readlane_b32 s8, v252, 52
	v_readlane_b32 s9, v252, 53
	s_lshl_b32 s16, s14, 11
	s_add_u32 s8, s8, s16
	s_addc_u32 s9, s9, 0
	s_lshr_b32 s17, s13, 6
	s_lshl_b32 s18, s17, 10
	s_cmpk_lt_i32 s13, 0x80
	s_cselect_b32 s15, 1, 0
	s_mov_b32 m0, s18
	s_nop 0
	global_load_lds_dwordx4 v50, s[6:7]
	s_add_u32 m0, s18, 4096
	s_nop 0
	global_load_lds_dwordx4 v51, s[6:7]
	s_add_u32 m0, s18, 8192
	s_nop 0
	global_load_lds_dwordx4 v52, s[6:7]
	s_add_u32 m0, s18, 12288
	s_nop 0
	global_load_lds_dwordx4 v53, s[6:7]
	s_cmp_eq_u32 s15, 0
	s_cbranch_scc1 .Lipa_noremp0
	s_add_u32 m0, s18, 16384
	s_nop 0
	global_load_lds_dwordx4 v54, s[6:7]
.Lipa_noremp0:
	s_add_u32 m0, s18, 18432
	s_nop 0
	global_load_lds_dwordx4 v50, s[8:9]
	s_add_u32 m0, s18, 22528
	s_nop 0
	global_load_lds_dwordx4 v51, s[8:9]
	s_add_u32 s6, s6, 64
	s_addc_u32 s7, s7, 0
	s_add_u32 s8, s8, 64
	s_addc_u32 s9, s9, 0
	s_add_u32 s18, s18, 26624
	s_cmp_ge_u32 s18, 53248
	s_cselect_b32 s16, 53248, 0
	s_sub_u32 s18, s18, s16
	v_and_b32_e32 v55, 15, v175
	s_and_b32 s16, s13, 64
	v_or_b32_e32 v56, s16, v55
	v_lshlrev_b32_e32 v180, 6, v56
	s_ashr_i32 s16, s13, 7
	s_mulk_i32 s16, 0x90
	v_or_b32_e32 v56, s16, v55
	v_lshlrev_b32_e32 v181, 6, v56
	v_lshrrev_b32_e32 v56, 1, v175
	v_and_b32_e32 v56, 6, v56
	s_movk_i32 s16, 0x78
	v_lshrrev_b32_e64 v56, v56, s16
	v_lshrrev_b32_e32 v57, 4, v175
	v_xor_b32_e32 v56, v56, v57
	v_lshlrev_b32_e32 v56, 4, v56
	v_and_b32_e32 v182, 48, v56
	v_mov_b32_e32 v2, 0
	v_mov_b32_e32 v3, 0
	v_mov_b32_e32 v4, 0
	v_mov_b32_e32 v5, 0
	v_mov_b32_e32 v6, 0
	v_mov_b32_e32 v7, 0
	v_mov_b32_e32 v8, 0
	v_mov_b32_e32 v9, 0
	v_mov_b32_e32 v10, 0
	v_mov_b32_e32 v11, 0
	v_mov_b32_e32 v12, 0
	v_mov_b32_e32 v13, 0
	v_mov_b32_e32 v14, 0
	v_mov_b32_e32 v15, 0
	v_mov_b32_e32 v16, 0
	v_mov_b32_e32 v17, 0
	v_mov_b32_e32 v18, 0
	v_mov_b32_e32 v19, 0
	v_mov_b32_e32 v20, 0
	v_mov_b32_e32 v21, 0
	v_mov_b32_e32 v22, 0
	v_mov_b32_e32 v23, 0
	v_mov_b32_e32 v24, 0
	v_mov_b32_e32 v25, 0
	v_mov_b32_e32 v26, 0
	v_mov_b32_e32 v27, 0
	v_mov_b32_e32 v28, 0
	v_mov_b32_e32 v29, 0
	v_mov_b32_e32 v30, 0
	v_mov_b32_e32 v31, 0
	v_mov_b32_e32 v32, 0
	v_mov_b32_e32 v33, 0
	v_mov_b32_e32 v34, 0
	v_mov_b32_e32 v35, 0
	v_mov_b32_e32 v36, 0
	v_mov_b32_e32 v37, 0
	v_mov_b32_e32 v38, 0
	v_mov_b32_e32 v39, 0
	v_mov_b32_e32 v40, 0
	v_mov_b32_e32 v41, 0
	v_mov_b32_e32 v42, 0
	v_mov_b32_e32 v43, 0
	v_mov_b32_e32 v44, 0
	v_mov_b32_e32 v45, 0
	v_mov_b32_e32 v46, 0
	v_mov_b32_e32 v47, 0
	v_mov_b32_e32 v48, 0
	v_mov_b32_e32 v49, 0
	v_mov_b32_e32 v58, 0
	v_mov_b32_e32 v59, 0
	v_mov_b32_e32 v60, 0
	v_mov_b32_e32 v61, 0
	v_mov_b32_e32 v62, 0
	v_mov_b32_e32 v63, 0
	v_mov_b32_e32 v64, 0
	v_mov_b32_e32 v65, 0
	v_mov_b32_e32 v78, 0
	v_mov_b32_e32 v79, 0
	v_mov_b32_e32 v80, 0
	v_mov_b32_e32 v81, 0
	v_mov_b32_e32 v82, 0
	v_mov_b32_e32 v83, 0
	v_mov_b32_e32 v84, 0
	v_mov_b32_e32 v85, 0
	v_mov_b32_e32 v86, 0
	v_mov_b32_e32 v87, 0
	v_mov_b32_e32 v88, 0
	v_mov_b32_e32 v89, 0
	v_mov_b32_e32 v90, 0
	v_mov_b32_e32 v91, 0
	v_mov_b32_e32 v92, 0
	v_mov_b32_e32 v93, 0
	v_mov_b32_e32 v94, 0
	v_mov_b32_e32 v95, 0
	v_mov_b32_e32 v96, 0
	v_mov_b32_e32 v97, 0
	v_mov_b32_e32 v98, 0
	v_mov_b32_e32 v99, 0
	v_mov_b32_e32 v100, 0
	v_mov_b32_e32 v101, 0
	v_mov_b32_e32 v106, 0
	v_mov_b32_e32 v107, 0
	v_mov_b32_e32 v108, 0
	v_mov_b32_e32 v109, 0
	v_mov_b32_e32 v110, 0
	v_mov_b32_e32 v111, 0
	v_mov_b32_e32 v112, 0
	v_mov_b32_e32 v113, 0
	v_mov_b32_e32 v114, 0
	v_mov_b32_e32 v115, 0
	v_mov_b32_e32 v116, 0
	v_mov_b32_e32 v117, 0
	v_mov_b32_e32 v122, 0
	v_mov_b32_e32 v123, 0
	v_mov_b32_e32 v124, 0
	v_mov_b32_e32 v125, 0
	v_mov_b32_e32 v126, 0
	v_mov_b32_e32 v127, 0
	v_mov_b32_e32 v128, 0
	v_mov_b32_e32 v129, 0
	v_mov_b32_e32 v130, 0
	v_mov_b32_e32 v131, 0
	v_mov_b32_e32 v132, 0
	v_mov_b32_e32 v133, 0
	v_mov_b32_e32 v134, 0
	v_mov_b32_e32 v135, 0
	v_mov_b32_e32 v136, 0
	v_mov_b32_e32 v137, 0
	v_mov_b32_e32 v138, 0
	v_mov_b32_e32 v139, 0
	v_mov_b32_e32 v140, 0
	v_mov_b32_e32 v141, 0
	v_mov_b32_e32 v142, 0
	v_mov_b32_e32 v143, 0
	v_mov_b32_e32 v144, 0
	v_mov_b32_e32 v145, 0
	v_mov_b32_e32 v146, 0
	v_mov_b32_e32 v147, 0
	v_mov_b32_e32 v148, 0
	v_mov_b32_e32 v149, 0
	v_mov_b32_e32 v150, 0
	v_mov_b32_e32 v151, 0
	v_mov_b32_e32 v152, 0
	v_mov_b32_e32 v153, 0
	v_mov_b32_e32 v154, 0
	v_mov_b32_e32 v155, 0
	v_mov_b32_e32 v156, 0
	v_mov_b32_e32 v157, 0
	v_mov_b32_e32 v158, 0
	v_mov_b32_e32 v159, 0
	v_mov_b32_e32 v160, 0
	v_mov_b32_e32 v161, 0
	v_mov_b32_e32 v162, 0
	v_mov_b32_e32 v163, 0
	v_mov_b32_e32 v164, 0
	v_mov_b32_e32 v165, 0
	v_mov_b32_e32 v166, 0
	v_mov_b32_e32 v167, 0
	v_mov_b32_e32 v168, 0
	v_mov_b32_e32 v169, 0
	v_mov_b32_e32 v170, 0
	v_mov_b32_e32 v171, 0
	v_mov_b32_e32 v172, 0
	v_mov_b32_e32 v173, 0
	s_mov_b32 s19, 0
	s_mov_b32 s5, 0
	s_waitcnt vmcnt(0)
	s_barrier
.Lipa_loop:
	s_cmp_ge_u32 s5, 31
	s_cbranch_scc1 .Lipa_body
	s_mov_b32 m0, s18
	s_nop 0
	global_load_lds_dwordx4 v50, s[6:7]
	s_add_u32 m0, s18, 4096
	s_nop 0
	global_load_lds_dwordx4 v51, s[6:7]
	s_add_u32 m0, s18, 8192
	s_nop 0
	global_load_lds_dwordx4 v52, s[6:7]
	s_add_u32 m0, s18, 12288
	s_nop 0
	global_load_lds_dwordx4 v53, s[6:7]
	s_cmp_eq_u32 s15, 0
	s_cbranch_scc1 .Lipa_noreml
	s_add_u32 m0, s18, 16384
	s_nop 0
	global_load_lds_dwordx4 v54, s[6:7]
.Lipa_noreml:
	s_add_u32 m0, s18, 18432
	s_nop 0
	global_load_lds_dwordx4 v50, s[8:9]
	s_add_u32 m0, s18, 22528
	s_nop 0
	global_load_lds_dwordx4 v51, s[8:9]
	s_add_u32 s6, s6, 64
	s_addc_u32 s7, s7, 0
	s_add_u32 s8, s8, 64
	s_addc_u32 s9, s9, 0
	s_add_u32 s18, s18, 26624
	s_cmp_ge_u32 s18, 53248
	s_cselect_b32 s16, 53248, 0
	s_sub_u32 s18, s18, s16
.Lipa_body:
	v_add_u32_e32 v183, s19, v182
	v_add_u32_e32 v200, v183, v180
	ds_read_b128 v[184:187], v200 offset:18432
	ds_read_b128 v[188:191], v200 offset:19456
	ds_read_b128 v[196:199], v200 offset:20480
	ds_read_b128 v[210:213], v200 offset:21504
	v_add_u32_e32 v183, v183, v181
	ds_read_b128 v[192:195], v183
	ds_read_b128 v[214:217], v183 offset:1024
	ds_read_b128 v[218:221], v183 offset:2048
	s_waitcnt lgkmcnt(2)
	v_mfma_f32_16x16x32_bf16 v[170:173], v[184:187], v[192:195], v[170:173]
	v_mfma_f32_16x16x32_bf16 v[166:169], v[188:191], v[192:195], v[166:169]
	v_mfma_f32_16x16x32_bf16 v[162:165], v[196:199], v[192:195], v[162:165]
	v_mfma_f32_16x16x32_bf16 v[158:161], v[210:213], v[192:195], v[158:161]
	ds_read_b128 v[192:195], v183 offset:3072
	s_waitcnt lgkmcnt(2)
	v_mfma_f32_16x16x32_bf16 v[154:157], v[184:187], v[214:217], v[154:157]
	v_mfma_f32_16x16x32_bf16 v[150:153], v[188:191], v[214:217], v[150:153]
	v_mfma_f32_16x16x32_bf16 v[146:149], v[196:199], v[214:217], v[146:149]
	v_mfma_f32_16x16x32_bf16 v[142:145], v[210:213], v[214:217], v[142:145]
	ds_read_b128 v[214:217], v183 offset:4096
	s_waitcnt lgkmcnt(2)
	v_mfma_f32_16x16x32_bf16 v[138:141], v[184:187], v[218:221], v[138:141]
	v_mfma_f32_16x16x32_bf16 v[134:137], v[188:191], v[218:221], v[134:137]
	v_mfma_f32_16x16x32_bf16 v[130:133], v[196:199], v[218:221], v[130:133]
	v_mfma_f32_16x16x32_bf16 v[126:129], v[210:213], v[218:221], v[126:129]
	ds_read_b128 v[218:221], v183 offset:5120
	s_waitcnt lgkmcnt(2)
	v_mfma_f32_16x16x32_bf16 v[122:125], v[184:187], v[192:195], v[122:125]
	v_mfma_f32_16x16x32_bf16 v[114:117], v[188:191], v[192:195], v[114:117]
	v_mfma_f32_16x16x32_bf16 v[110:113], v[196:199], v[192:195], v[110:113]
	v_mfma_f32_16x16x32_bf16 v[106:109], v[210:213], v[192:195], v[106:109]
	ds_read_b128 v[192:195], v183 offset:6144
	s_waitcnt lgkmcnt(2)
	v_mfma_f32_16x16x32_bf16 v[98:101], v[184:187], v[214:217], v[98:101]
	v_mfma_f32_16x16x32_bf16 v[94:97], v[188:191], v[214:217], v[94:97]
	v_mfma_f32_16x16x32_bf16 v[90:93], v[196:199], v[214:217], v[90:93]
	v_mfma_f32_16x16x32_bf16 v[86:89], v[210:213], v[214:217], v[86:89]
	ds_read_b128 v[214:217], v183 offset:7168
	s_waitcnt lgkmcnt(2)
	v_mfma_f32_16x16x32_bf16 v[82:85], v[184:187], v[218:221], v[82:85]
	v_mfma_f32_16x16x32_bf16 v[78:81], v[188:191], v[218:221], v[78:81]
	v_mfma_f32_16x16x32_bf16 v[62:65], v[196:199], v[218:221], v[62:65]
	v_mfma_f32_16x16x32_bf16 v[58:61], v[210:213], v[218:221], v[58:61]
	ds_read_b128 v[218:221], v183 offset:8192
	s_waitcnt lgkmcnt(2)
	v_mfma_f32_16x16x32_bf16 v[46:49], v[184:187], v[192:195], v[46:49]
	v_mfma_f32_16x16x32_bf16 v[42:45], v[188:191], v[192:195], v[42:45]
	v_mfma_f32_16x16x32_bf16 v[38:41], v[196:199], v[192:195], v[38:41]
	v_mfma_f32_16x16x32_bf16 v[34:37], v[210:213], v[192:195], v[34:37]
	s_waitcnt lgkmcnt(1)
	v_mfma_f32_16x16x32_bf16 v[30:33], v[184:187], v[214:217], v[30:33]
	v_mfma_f32_16x16x32_bf16 v[26:29], v[188:191], v[214:217], v[26:29]
	v_mfma_f32_16x16x32_bf16 v[22:25], v[196:199], v[214:217], v[22:25]
	v_mfma_f32_16x16x32_bf16 v[18:21], v[210:213], v[214:217], v[18:21]
	s_waitcnt lgkmcnt(0)
	v_mfma_f32_16x16x32_bf16 v[14:17], v[184:187], v[218:221], v[14:17]
	v_mfma_f32_16x16x32_bf16 v[10:13], v[188:191], v[218:221], v[10:13]
	v_mfma_f32_16x16x32_bf16 v[6:9], v[196:199], v[218:221], v[6:9]
	v_mfma_f32_16x16x32_bf16 v[2:5], v[210:213], v[218:221], v[2:5]
	s_add_u32 s19, s19, 26624
	s_cmp_ge_u32 s19, 53248
	s_cselect_b32 s16, 53248, 0
	s_sub_u32 s19, s19, s16
	s_waitcnt vmcnt(0)
	s_barrier
	s_add_u32 s5, s5, 1
	s_cmp_lt_u32 s5, 32
	s_cbranch_scc1 .Lipa_loop

.LBB0_731:
	s_and_b64 vcc, exec, s[0:1]
	s_cbranch_vccz .LBB0_693
	v_readfirstlane_b32 s13, v175
	v_lshrrev_b32_e32 v43, 3, v175
	v_and_b32_e32 v43, 6, v43
	s_movk_i32 s16, 0x78
	v_lshrrev_b32_e64 v43, v43, s16
	v_xor_b32_e32 v43, v43, v175
	v_and_b32_e32 v43, 3, v43
	v_lshlrev_b32_e32 v43, 4, v43
	v_lshrrev_b32_e32 v44, 2, v175
	v_lshl_or_b32 v38, v44, 11, v43
	v_add_u32_e32 v39, 0x20000, v38
	v_add_u32_e32 v40, 0x40000, v38
	v_add_u32_e32 v41, 0x60000, v38
	v_add_u32_e32 v42, 0x80000, v38
	s_lshl_b32 s16, s12, 11
	s_add_u32 s6, s96, s16
	s_addc_u32 s7, s97, 0
	v_readlane_b32 s8, v252, 52
	v_readlane_b32 s9, v252, 53
	s_lshl_b32 s16, s14, 11
	s_add_u32 s8, s8, s16
	s_addc_u32 s9, s9, 0
	s_lshr_b32 s17, s13, 6
	s_lshl_b32 s18, s17, 10
	s_cmpk_lt_i32 s13, 0x80
	s_cselect_b32 s15, 1, 0
	s_mov_b32 m0, s18
	s_nop 0
	global_load_lds_dwordx4 v38, s[6:7]
	s_add_u32 m0, s18, 4096
	s_nop 0
	global_load_lds_dwordx4 v39, s[6:7]
	s_add_u32 m0, s18, 8192
	s_nop 0
	global_load_lds_dwordx4 v40, s[6:7]
	s_add_u32 m0, s18, 12288
	s_nop 0
	global_load_lds_dwordx4 v41, s[6:7]
	s_cmp_eq_u32 s15, 0
	s_cbranch_scc1 .Lipb_noremp0
	s_add_u32 m0, s18, 16384
	s_nop 0
	global_load_lds_dwordx4 v42, s[6:7]
.Lipb_noremp0:
	s_add_u32 m0, s18, 18432
	s_nop 0
	global_load_lds_dwordx4 v38, s[8:9]
	s_add_u32 m0, s18, 22528
	s_nop 0
	global_load_lds_dwordx4 v39, s[8:9]
	s_add_u32 s6, s6, 64
	s_addc_u32 s7, s7, 0
	s_add_u32 s8, s8, 64
	s_addc_u32 s9, s9, 0
	s_add_u32 s18, s18, 26624
	s_cmp_ge_u32 s18, 53248
	s_cselect_b32 s16, 53248, 0
	s_sub_u32 s18, s18, s16
	v_and_b32_e32 v43, 15, v175
	s_and_b32 s16, s13, 64
	v_or_b32_e32 v44, s16, v43
	v_lshlrev_b32_e32 v180, 6, v44
	s_ashr_i32 s16, s13, 7
	s_mulk_i32 s16, 0x90
	v_or_b32_e32 v44, s16, v43
	v_lshlrev_b32_e32 v181, 6, v44
	v_lshrrev_b32_e32 v44, 1, v175
	v_and_b32_e32 v44, 6, v44
	s_movk_i32 s16, 0x78
	v_lshrrev_b32_e64 v44, v44, s16
	v_lshrrev_b32_e32 v45, 4, v175
	v_xor_b32_e32 v44, v44, v45
	v_lshlrev_b32_e32 v44, 4, v44
	v_and_b32_e32 v182, 48, v44
	v_mov_b32_e32 v2, 0
	v_mov_b32_e32 v3, 0
	v_mov_b32_e32 v4, 0
	v_mov_b32_e32 v5, 0
	v_mov_b32_e32 v14, 0
	v_mov_b32_e32 v15, 0
	v_mov_b32_e32 v16, 0
	v_mov_b32_e32 v17, 0
	v_mov_b32_e32 v50, 0
	v_mov_b32_e32 v51, 0
	v_mov_b32_e32 v52, 0
	v_mov_b32_e32 v53, 0
	v_mov_b32_e32 v98, 0
	v_mov_b32_e32 v99, 0
	v_mov_b32_e32 v100, 0
	v_mov_b32_e32 v101, 0
	v_mov_b32_e32 v6, 0
	v_mov_b32_e32 v7, 0
	v_mov_b32_e32 v8, 0
	v_mov_b32_e32 v9, 0
	v_mov_b32_e32 v26, 0
	v_mov_b32_e32 v27, 0
	v_mov_b32_e32 v28, 0
	v_mov_b32_e32 v29, 0
	v_mov_b32_e32 v78, 0
	v_mov_b32_e32 v79, 0
	v_mov_b32_e32 v80, 0
	v_mov_b32_e32 v81, 0
	v_mov_b32_e32 v118, 0
	v_mov_b32_e32 v119, 0
	v_mov_b32_e32 v120, 0
	v_mov_b32_e32 v121, 0
	v_mov_b32_e32 v10, 0
	v_mov_b32_e32 v11, 0
	v_mov_b32_e32 v12, 0
	v_mov_b32_e32 v13, 0
	v_mov_b32_e32 v30, 0
	v_mov_b32_e32 v31, 0
	v_mov_b32_e32 v32, 0
	v_mov_b32_e32 v33, 0
	v_mov_b32_e32 v86, 0
	v_mov_b32_e32 v87, 0
	v_mov_b32_e32 v88, 0
	v_mov_b32_e32 v89, 0
	v_mov_b32_e32 v130, 0
	v_mov_b32_e32 v131, 0
	v_mov_b32_e32 v132, 0
	v_mov_b32_e32 v133, 0
	v_mov_b32_e32 v18, 0
	v_mov_b32_e32 v19, 0
	v_mov_b32_e32 v20, 0
	v_mov_b32_e32 v21, 0
	v_mov_b32_e32 v54, 0
	v_mov_b32_e32 v55, 0
	v_mov_b32_e32 v56, 0
	v_mov_b32_e32 v57, 0
	v_mov_b32_e32 v102, 0
	v_mov_b32_e32 v103, 0
	v_mov_b32_e32 v104, 0
	v_mov_b32_e32 v105, 0
	v_mov_b32_e32 v142, 0
	v_mov_b32_e32 v143, 0
	v_mov_b32_e32 v144, 0
	v_mov_b32_e32 v145, 0
	v_mov_b32_e32 v22, 0
	v_mov_b32_e32 v23, 0
	v_mov_b32_e32 v24, 0
	v_mov_b32_e32 v25, 0
	v_mov_b32_e32 v70, 0
	v_mov_b32_e32 v71, 0
	v_mov_b32_e32 v72, 0
	v_mov_b32_e32 v73, 0
	v_mov_b32_e32 v110, 0
	v_mov_b32_e32 v111, 0
	v_mov_b32_e32 v112, 0
	v_mov_b32_e32 v113, 0
	v_mov_b32_e32 v146, 0
	v_mov_b32_e32 v147, 0
	v_mov_b32_e32 v148, 0
	v_mov_b32_e32 v149, 0
	v_mov_b32_e32 v34, 0
	v_mov_b32_e32 v35, 0
	v_mov_b32_e32 v36, 0
	v_mov_b32_e32 v37, 0
	v_mov_b32_e32 v90, 0
	v_mov_b32_e32 v91, 0
	v_mov_b32_e32 v92, 0
	v_mov_b32_e32 v93, 0
	v_mov_b32_e32 v134, 0
	v_mov_b32_e32 v135, 0
	v_mov_b32_e32 v136, 0
	v_mov_b32_e32 v137, 0
	v_mov_b32_e32 v158, 0
	v_mov_b32_e32 v159, 0
	v_mov_b32_e32 v160, 0
	v_mov_b32_e32 v161, 0
	v_mov_b32_e32 v46, 0
	v_mov_b32_e32 v47, 0
	v_mov_b32_e32 v48, 0
	v_mov_b32_e32 v49, 0
	v_mov_b32_e32 v94, 0
	v_mov_b32_e32 v95, 0
	v_mov_b32_e32 v96, 0
	v_mov_b32_e32 v97, 0
	v_mov_b32_e32 v138, 0
	v_mov_b32_e32 v139, 0
	v_mov_b32_e32 v140, 0
	v_mov_b32_e32 v141, 0
	v_mov_b32_e32 v162, 0
	v_mov_b32_e32 v163, 0
	v_mov_b32_e32 v164, 0
	v_mov_b32_e32 v165, 0
	v_mov_b32_e32 v74, 0
	v_mov_b32_e32 v75, 0
	v_mov_b32_e32 v76, 0
	v_mov_b32_e32 v77, 0
	v_mov_b32_e32 v114, 0
	v_mov_b32_e32 v115, 0
	v_mov_b32_e32 v116, 0
	v_mov_b32_e32 v117, 0
	v_mov_b32_e32 v150, 0
	v_mov_b32_e32 v151, 0
	v_mov_b32_e32 v152, 0
	v_mov_b32_e32 v153, 0
	v_mov_b32_e32 v166, 0
	v_mov_b32_e32 v167, 0
	v_mov_b32_e32 v168, 0
	v_mov_b32_e32 v169, 0
	v_mov_b32_e32 v82, 0
	v_mov_b32_e32 v83, 0
	v_mov_b32_e32 v84, 0
	v_mov_b32_e32 v85, 0
	v_mov_b32_e32 v122, 0
	v_mov_b32_e32 v123, 0
	v_mov_b32_e32 v124, 0
	v_mov_b32_e32 v125, 0
	v_mov_b32_e32 v154, 0
	v_mov_b32_e32 v155, 0
	v_mov_b32_e32 v156, 0
	v_mov_b32_e32 v157, 0
	v_mov_b32_e32 v170, 0
	v_mov_b32_e32 v171, 0
	v_mov_b32_e32 v172, 0
	v_mov_b32_e32 v173, 0
	s_mov_b32 s19, 0
	s_mov_b32 s5, 0
	s_waitcnt vmcnt(0)
	s_barrier
.Lipb_loop:
	s_cmp_ge_u32 s5, 31
	s_cbranch_scc1 .Lipb_body
	s_mov_b32 m0, s18
	s_nop 0
	global_load_lds_dwordx4 v38, s[6:7]
	s_add_u32 m0, s18, 4096
	s_nop 0
	global_load_lds_dwordx4 v39, s[6:7]
	s_add_u32 m0, s18, 8192
	s_nop 0
	global_load_lds_dwordx4 v40, s[6:7]
	s_add_u32 m0, s18, 12288
	s_nop 0
	global_load_lds_dwordx4 v41, s[6:7]
	s_cmp_eq_u32 s15, 0
	s_cbranch_scc1 .Lipb_noreml
	s_add_u32 m0, s18, 16384
	s_nop 0
	global_load_lds_dwordx4 v42, s[6:7]
.Lipb_noreml:
	s_add_u32 m0, s18, 18432
	s_nop 0
	global_load_lds_dwordx4 v38, s[8:9]
	s_add_u32 m0, s18, 22528
	s_nop 0
	global_load_lds_dwordx4 v39, s[8:9]
	s_add_u32 s6, s6, 64
	s_addc_u32 s7, s7, 0
	s_add_u32 s8, s8, 64
	s_addc_u32 s9, s9, 0
	s_add_u32 s18, s18, 26624
	s_cmp_ge_u32 s18, 53248
	s_cselect_b32 s16, 53248, 0
	s_sub_u32 s18, s18, s16
.Lipb_body:
	v_add_u32_e32 v183, s19, v182
	v_add_u32_e32 v200, v183, v181
	ds_read_b128 v[184:187], v200
	ds_read_b128 v[214:217], v200 offset:1024
	ds_read_b128 v[218:221], v200 offset:2048
	v_add_u32_e32 v183, v183, v180
	ds_read_b128 v[188:191], v183 offset:18432
	ds_read_b128 v[192:195], v183 offset:19456
	ds_read_b128 v[196:199], v183 offset:20480
	ds_read_b128 v[210:213], v183 offset:21504
	s_waitcnt lgkmcnt(3)
	v_mfma_f32_16x16x32_bf16 v[170:173], v[184:187], v[188:191], v[170:173]
	s_waitcnt lgkmcnt(2)
	v_mfma_f32_16x16x32_bf16 v[154:157], v[184:187], v[192:195], v[154:157]
	s_waitcnt lgkmcnt(1)
	v_mfma_f32_16x16x32_bf16 v[122:125], v[184:187], v[196:199], v[122:125]
	s_waitcnt lgkmcnt(0)
	v_mfma_f32_16x16x32_bf16 v[82:85], v[184:187], v[210:213], v[82:85]
	ds_read_b128 v[184:187], v200 offset:3072
	v_mfma_f32_16x16x32_bf16 v[166:169], v[214:217], v[188:191], v[166:169]
	v_mfma_f32_16x16x32_bf16 v[150:153], v[214:217], v[192:195], v[150:153]
	v_mfma_f32_16x16x32_bf16 v[114:117], v[214:217], v[196:199], v[114:117]
	v_mfma_f32_16x16x32_bf16 v[74:77], v[214:217], v[210:213], v[74:77]
	ds_read_b128 v[214:217], v200 offset:4096
	v_mfma_f32_16x16x32_bf16 v[162:165], v[218:221], v[188:191], v[162:165]
	v_mfma_f32_16x16x32_bf16 v[138:141], v[218:221], v[192:195], v[138:141]
	v_mfma_f32_16x16x32_bf16 v[94:97], v[218:221], v[196:199], v[94:97]
	v_mfma_f32_16x16x32_bf16 v[46:49], v[218:221], v[210:213], v[46:49]
	ds_read_b128 v[218:221], v200 offset:5120
	s_waitcnt lgkmcnt(2)
	v_mfma_f32_16x16x32_bf16 v[158:161], v[184:187], v[188:191], v[158:161]
	v_mfma_f32_16x16x32_bf16 v[134:137], v[184:187], v[192:195], v[134:137]
	v_mfma_f32_16x16x32_bf16 v[90:93], v[184:187], v[196:199], v[90:93]
	v_mfma_f32_16x16x32_bf16 v[34:37], v[184:187], v[210:213], v[34:37]
	ds_read_b128 v[184:187], v200 offset:6144
	s_waitcnt lgkmcnt(2)
	v_mfma_f32_16x16x32_bf16 v[146:149], v[214:217], v[188:191], v[146:149]
	v_mfma_f32_16x16x32_bf16 v[110:113], v[214:217], v[192:195], v[110:113]
	v_mfma_f32_16x16x32_bf16 v[70:73], v[214:217], v[196:199], v[70:73]
	v_mfma_f32_16x16x32_bf16 v[22:25], v[214:217], v[210:213], v[22:25]
	ds_read_b128 v[214:217], v200 offset:7168
	s_waitcnt lgkmcnt(2)
	v_mfma_f32_16x16x32_bf16 v[142:145], v[218:221], v[188:191], v[142:145]
	v_mfma_f32_16x16x32_bf16 v[102:105], v[218:221], v[192:195], v[102:105]
	v_mfma_f32_16x16x32_bf16 v[54:57], v[218:221], v[196:199], v[54:57]
	v_mfma_f32_16x16x32_bf16 v[18:21], v[218:221], v[210:213], v[18:21]
	ds_read_b128 v[218:221], v200 offset:8192
	s_waitcnt lgkmcnt(2)
	v_mfma_f32_16x16x32_bf16 v[130:133], v[184:187], v[188:191], v[130:133]
	v_mfma_f32_16x16x32_bf16 v[86:89], v[184:187], v[192:195], v[86:89]
	v_mfma_f32_16x16x32_bf16 v[30:33], v[184:187], v[196:199], v[30:33]
	v_mfma_f32_16x16x32_bf16 v[10:13], v[184:187], v[210:213], v[10:13]
	s_waitcnt lgkmcnt(1)
	v_mfma_f32_16x16x32_bf16 v[118:121], v[214:217], v[188:191], v[118:121]
	v_mfma_f32_16x16x32_bf16 v[78:81], v[214:217], v[192:195], v[78:81]
	v_mfma_f32_16x16x32_bf16 v[26:29], v[214:217], v[196:199], v[26:29]
	v_mfma_f32_16x16x32_bf16 v[6:9], v[214:217], v[210:213], v[6:9]
	s_waitcnt lgkmcnt(0)
	v_mfma_f32_16x16x32_bf16 v[98:101], v[218:221], v[188:191], v[98:101]
	v_mfma_f32_16x16x32_bf16 v[50:53], v[218:221], v[192:195], v[50:53]
	v_mfma_f32_16x16x32_bf16 v[14:17], v[218:221], v[196:199], v[14:17]
	v_mfma_f32_16x16x32_bf16 v[2:5], v[218:221], v[210:213], v[2:5]
	s_add_u32 s19, s19, 26624
	s_cmp_ge_u32 s19, 53248
	s_cselect_b32 s16, 53248, 0
	s_sub_u32 s19, s19, s16
	s_waitcnt vmcnt(0)
	s_barrier
	s_add_u32 s5, s5, 1
	s_cmp_lt_u32 s5, 32
	s_cbranch_scc1 .Lipb_loop
	s_branch .LBB0_692

.LBB0_761:
	s_and_b64 vcc, exec, s[0:1]
	s_cbranch_vccz .LBB0_763
	v_readlane_b32 s0, v250, 26
	v_readlane_b32 s1, v250, 27
	s_nop 0
	s_andn2_b64 vcc, exec, s[0:1]
	s_cmpk_lt_i32 s73, 0x110
	s_cbranch_scc1 .Lprep_filt
	s_sub_i32 s15, s73, 0x110
	s_movk_i32 s101, 0x112
	s_cmp_lt_i32 s15, 2
	s_cbranch_scc1 .Lprep_set
	s_addk_i32 s15, 0x112
	s_movk_i32 s101, 0xf0
	s_branch .Lprep_set
.Lprep_filt:
	s_add_i32 s15, s73, 2
	s_movk_i32 s101, 0x1000
.Lprep_set:
	s_sub_i32 s14, 0x111, s15
	s_mul_i32 s0, s15, 0x3a20
	s_mul_hi_i32 s1, s15, 0x3a20
	v_readlane_b32 s2, v251, 52
	v_readlane_b32 s3, v251, 53
	s_add_u32 s2, s2, s0
	s_addc_u32 s3, s3, s1
	s_cbranch_vccz .LBB0_778

.LBB0_777:
	s_add_i32 s15, s15, s101
	s_sub_i32 s14, s14, s101
	s_mul_i32 s0, s101, 0x3a20
	s_add_u32 s2, s2, s0
	s_mul_hi_i32 s0, s101, 0x3a20
	s_addc_u32 s3, s3, s0
	s_movk_i32 s101, 0xf0
	s_cmpk_gt_i32 s15, 0x791
	s_cbranch_scc1 .LBB0_763

.LBB0_880:
	v_readlane_b32 s56, v252, 7
	v_readlane_b32 s57, v252, 8
	v_readlane_b32 s60, v252, 11
	v_readlane_b32 s61, v252, 12
	v_readfirstlane_b32 s1, v175
	s_ashr_i32 s0, s1, 7
	s_mulk_i32 s0, 0x90
	s_add_i32 s0, s0, s9
	v_lshrrev_b32_e32 v1, 2, v175
	v_and_b32_e32 v1, 12, v1
	v_and_or_b32 v1, s1, 64, v1
	v_or_b32_e32 v1, s10, v1
	v_lshlrev_b32_e32 v1, 2, v1
	v_and_b32_e32 v0, 15, v175
	v_lshl_or_b32 v0, v0, 12, v1
	s_mov_b32 s11, s0
	s_ashr_i32 s13, s11, 11
	s_mulk_i32 s13, 0x3000
	s_and_b32 s12, s11, 0x3fff
	s_lshl_b32 s12, s12, 12
	s_cmpk_lt_i32 s11, 0x4000
	s_cselect_b32 s2, s56, s60
	s_cselect_b32 s3, s57, s61
	s_cselect_b32 s62, s48, s24
	s_cselect_b32 s63, s49, s25
	s_cselect_b32 s13, s13, 0x18000
	s_add_u32 s2, s2, s12
	s_addc_u32 s3, s3, 0
	s_add_u32 s62, s62, s12
	s_addc_u32 s63, s63, 0
	s_add_u32 s4, s34, s13
	s_addc_u32 s5, s35, 0
	global_load_dwordx4 v[180:183], v1, s[4:5]
	global_load_dwordx4 v[130:133], v0, s[2:3]
	global_load_dwordx4 v[184:187], v1, s[4:5] offset:64
	global_load_dwordx4 v[134:137], v0, s[2:3] offset:64
	global_load_dwordx4 v[188:191], v1, s[4:5] offset:128
	global_load_dwordx4 v[138:141], v0, s[2:3] offset:128
	global_load_dwordx4 v[192:195], v1, s[4:5] offset:192
	global_load_dwordx4 v[142:145], v0, s[2:3] offset:192
	s_add_i32 s11, s0, 16
	s_ashr_i32 s13, s11, 11
	s_mulk_i32 s13, 0x3000
	s_and_b32 s12, s11, 0x3fff
	s_lshl_b32 s12, s12, 12
	s_cmpk_lt_i32 s11, 0x4000
	s_cselect_b32 s2, s56, s60
	s_cselect_b32 s3, s57, s61
	s_cselect_b32 s64, s48, s24
	s_cselect_b32 s65, s49, s25
	s_cselect_b32 s13, s13, 0x18000
	s_add_u32 s2, s2, s12
	s_addc_u32 s3, s3, 0
	s_add_u32 s64, s64, s12
	s_addc_u32 s65, s65, 0
	s_add_u32 s4, s34, s13
	s_addc_u32 s5, s35, 0
	global_load_dwordx4 v[196:199], v1, s[4:5]
	global_load_dwordx4 v[146:149], v0, s[2:3]
	global_load_dwordx4 v[200:203], v1, s[4:5] offset:64
	global_load_dwordx4 v[154:157], v0, s[2:3] offset:64
	global_load_dwordx4 v[208:211], v1, s[4:5] offset:128
	global_load_dwordx4 v[166:169], v0, s[2:3] offset:128
	global_load_dwordx4 v[212:215], v1, s[4:5] offset:192
	global_load_dwordx4 v[176:179], v0, s[2:3] offset:192
	s_waitcnt vmcnt(8)
	v_pk_fma_f32 v[170:171], v[170:171], v[180:181], v[130:131]
	v_pk_fma_f32 v[172:173], v[172:173], v[182:183], v[132:133]
	v_pk_fma_f32 v[162:163], v[162:163], v[184:185], v[134:135]
	v_pk_fma_f32 v[164:165], v[164:165], v[186:187], v[136:137]
	v_pk_fma_f32 v[158:159], v[158:159], v[188:189], v[138:139]
	v_pk_fma_f32 v[160:161], v[160:161], v[190:191], v[140:141]
	v_pk_fma_f32 v[150:151], v[150:151], v[192:193], v[142:143]
	v_pk_fma_f32 v[152:153], v[152:153], v[194:195], v[144:145]
	global_store_dwordx4 v0, v[170:173], s[62:63]
	global_store_dwordx4 v0, v[162:165], s[62:63] offset:64
	global_store_dwordx4 v0, v[158:161], s[62:63] offset:128
	global_store_dwordx4 v0, v[150:153], s[62:63] offset:192
	s_add_i32 s11, s0, 32
	s_ashr_i32 s13, s11, 11
	s_mulk_i32 s13, 0x3000
	s_and_b32 s12, s11, 0x3fff
	s_lshl_b32 s12, s12, 12
	s_cmpk_lt_i32 s11, 0x4000
	s_cselect_b32 s2, s56, s60
	s_cselect_b32 s3, s57, s61
	s_cselect_b32 s62, s48, s24
	s_cselect_b32 s63, s49, s25
	s_cselect_b32 s13, s13, 0x18000
	s_add_u32 s2, s2, s12
	s_addc_u32 s3, s3, 0
	s_add_u32 s62, s62, s12
	s_addc_u32 s63, s63, 0
	s_add_u32 s4, s34, s13
	s_addc_u32 s5, s35, 0
	global_load_dwordx4 v[180:183], v1, s[4:5]
	global_load_dwordx4 v[130:133], v0, s[2:3]
	global_load_dwordx4 v[184:187], v1, s[4:5] offset:64
	global_load_dwordx4 v[134:137], v0, s[2:3] offset:64
	global_load_dwordx4 v[188:191], v1, s[4:5] offset:128
	global_load_dwordx4 v[138:141], v0, s[2:3] offset:128
	global_load_dwordx4 v[192:195], v1, s[4:5] offset:192
	global_load_dwordx4 v[142:145], v0, s[2:3] offset:192
	s_waitcnt vmcnt(12)
	v_pk_fma_f32 v[126:127], v[126:127], v[196:197], v[146:147]
	v_pk_fma_f32 v[128:129], v[128:129], v[198:199], v[148:149]
	v_pk_fma_f32 v[122:123], v[122:123], v[200:201], v[154:155]
	v_pk_fma_f32 v[124:125], v[124:125], v[202:203], v[156:157]
	v_pk_fma_f32 v[118:119], v[118:119], v[208:209], v[166:167]
	v_pk_fma_f32 v[120:121], v[120:121], v[210:211], v[168:169]
	v_pk_fma_f32 v[114:115], v[114:115], v[212:213], v[176:177]
	v_pk_fma_f32 v[116:117], v[116:117], v[214:215], v[178:179]
	global_store_dwordx4 v0, v[126:129], s[64:65]
	global_store_dwordx4 v0, v[122:125], s[64:65] offset:64
	global_store_dwordx4 v0, v[118:121], s[64:65] offset:128
	global_store_dwordx4 v0, v[114:117], s[64:65] offset:192
	s_add_i32 s11, s0, 48
	s_ashr_i32 s13, s11, 11
	s_mulk_i32 s13, 0x3000
	s_and_b32 s12, s11, 0x3fff
	s_lshl_b32 s12, s12, 12
	s_cmpk_lt_i32 s11, 0x4000
	s_cselect_b32 s2, s56, s60
	s_cselect_b32 s3, s57, s61
	s_cselect_b32 s64, s48, s24
	s_cselect_b32 s65, s49, s25
	s_cselect_b32 s13, s13, 0x18000
	s_add_u32 s2, s2, s12
	s_addc_u32 s3, s3, 0
	s_add_u32 s64, s64, s12
	s_addc_u32 s65, s65, 0
	s_add_u32 s4, s34, s13
	s_addc_u32 s5, s35, 0
	global_load_dwordx4 v[196:199], v1, s[4:5]
	global_load_dwordx4 v[146:149], v0, s[2:3]
	global_load_dwordx4 v[200:203], v1, s[4:5] offset:64
	global_load_dwordx4 v[154:157], v0, s[2:3] offset:64
	global_load_dwordx4 v[208:211], v1, s[4:5] offset:128
	global_load_dwordx4 v[166:169], v0, s[2:3] offset:128
	global_load_dwordx4 v[212:215], v1, s[4:5] offset:192
	global_load_dwordx4 v[176:179], v0, s[2:3] offset:192
	s_waitcnt vmcnt(12)
	v_pk_fma_f32 v[110:111], v[110:111], v[180:181], v[130:131]
	v_pk_fma_f32 v[112:113], v[112:113], v[182:183], v[132:133]
	v_pk_fma_f32 v[106:107], v[106:107], v[184:185], v[134:135]
	v_pk_fma_f32 v[108:109], v[108:109], v[186:187], v[136:137]
	v_pk_fma_f32 v[102:103], v[102:103], v[188:189], v[138:139]
	v_pk_fma_f32 v[104:105], v[104:105], v[190:191], v[140:141]
	v_pk_fma_f32 v[98:99], v[98:99], v[192:193], v[142:143]
	v_pk_fma_f32 v[100:101], v[100:101], v[194:195], v[144:145]
	global_store_dwordx4 v0, v[110:113], s[62:63]
	global_store_dwordx4 v0, v[106:109], s[62:63] offset:64
	global_store_dwordx4 v0, v[102:105], s[62:63] offset:128
	global_store_dwordx4 v0, v[98:101], s[62:63] offset:192
	s_add_i32 s11, s0, 64
	s_ashr_i32 s13, s11, 11
	s_mulk_i32 s13, 0x3000
	s_and_b32 s12, s11, 0x3fff
	s_lshl_b32 s12, s12, 12
	s_cmpk_lt_i32 s11, 0x4000
	s_cselect_b32 s2, s56, s60
	s_cselect_b32 s3, s57, s61
	s_cselect_b32 s62, s48, s24
	s_cselect_b32 s63, s49, s25
	s_cselect_b32 s13, s13, 0x18000
	s_add_u32 s2, s2, s12
	s_addc_u32 s3, s3, 0
	s_add_u32 s62, s62, s12
	s_addc_u32 s63, s63, 0
	s_add_u32 s4, s34, s13
	s_addc_u32 s5, s35, 0
	global_load_dwordx4 v[180:183], v1, s[4:5]
	global_load_dwordx4 v[130:133], v0, s[2:3]
	global_load_dwordx4 v[184:187], v1, s[4:5] offset:64
	global_load_dwordx4 v[134:137], v0, s[2:3] offset:64
	global_load_dwordx4 v[188:191], v1, s[4:5] offset:128
	global_load_dwordx4 v[138:141], v0, s[2:3] offset:128
	global_load_dwordx4 v[192:195], v1, s[4:5] offset:192
	global_load_dwordx4 v[142:145], v0, s[2:3] offset:192
	s_waitcnt vmcnt(12)
	v_pk_fma_f32 v[94:95], v[94:95], v[196:197], v[146:147]
	v_pk_fma_f32 v[96:97], v[96:97], v[198:199], v[148:149]
	v_pk_fma_f32 v[90:91], v[90:91], v[200:201], v[154:155]
	v_pk_fma_f32 v[92:93], v[92:93], v[202:203], v[156:157]
	v_pk_fma_f32 v[86:87], v[86:87], v[208:209], v[166:167]
	v_pk_fma_f32 v[88:89], v[88:89], v[210:211], v[168:169]
	v_pk_fma_f32 v[82:83], v[82:83], v[212:213], v[176:177]
	v_pk_fma_f32 v[84:85], v[84:85], v[214:215], v[178:179]
	global_store_dwordx4 v0, v[94:97], s[64:65]
	global_store_dwordx4 v0, v[90:93], s[64:65] offset:64
	global_store_dwordx4 v0, v[86:89], s[64:65] offset:128
	global_store_dwordx4 v0, v[82:85], s[64:65] offset:192
	s_add_i32 s11, s0, 80
	s_ashr_i32 s13, s11, 11
	s_mulk_i32 s13, 0x3000
	s_and_b32 s12, s11, 0x3fff
	s_lshl_b32 s12, s12, 12
	s_cmpk_lt_i32 s11, 0x4000
	s_cselect_b32 s2, s56, s60
	s_cselect_b32 s3, s57, s61
	s_cselect_b32 s64, s48, s24
	s_cselect_b32 s65, s49, s25
	s_cselect_b32 s13, s13, 0x18000
	s_add_u32 s2, s2, s12
	s_addc_u32 s3, s3, 0
	s_add_u32 s64, s64, s12
	s_addc_u32 s65, s65, 0
	s_add_u32 s4, s34, s13
	s_addc_u32 s5, s35, 0
	global_load_dwordx4 v[196:199], v1, s[4:5]
	global_load_dwordx4 v[146:149], v0, s[2:3]
	global_load_dwordx4 v[200:203], v1, s[4:5] offset:64
	global_load_dwordx4 v[154:157], v0, s[2:3] offset:64
	global_load_dwordx4 v[208:211], v1, s[4:5] offset:128
	global_load_dwordx4 v[166:169], v0, s[2:3] offset:128
	global_load_dwordx4 v[212:215], v1, s[4:5] offset:192
	global_load_dwordx4 v[176:179], v0, s[2:3] offset:192
	s_waitcnt vmcnt(12)
	v_pk_fma_f32 v[78:79], v[78:79], v[180:181], v[130:131]
	v_pk_fma_f32 v[80:81], v[80:81], v[182:183], v[132:133]
	v_pk_fma_f32 v[74:75], v[74:75], v[184:185], v[134:135]
	v_pk_fma_f32 v[76:77], v[76:77], v[186:187], v[136:137]
	v_pk_fma_f32 v[70:71], v[70:71], v[188:189], v[138:139]
	v_pk_fma_f32 v[72:73], v[72:73], v[190:191], v[140:141]
	v_pk_fma_f32 v[66:67], v[66:67], v[192:193], v[142:143]
	v_pk_fma_f32 v[68:69], v[68:69], v[194:195], v[144:145]
	global_store_dwordx4 v0, v[78:81], s[62:63]
	global_store_dwordx4 v0, v[74:77], s[62:63] offset:64
	global_store_dwordx4 v0, v[70:73], s[62:63] offset:128
	global_store_dwordx4 v0, v[66:69], s[62:63] offset:192
	s_add_i32 s11, s0, 96
	s_ashr_i32 s13, s11, 11
	s_mulk_i32 s13, 0x3000
	s_and_b32 s12, s11, 0x3fff
	s_lshl_b32 s12, s12, 12
	s_cmpk_lt_i32 s11, 0x4000
	s_cselect_b32 s2, s56, s60
	s_cselect_b32 s3, s57, s61
	s_cselect_b32 s62, s48, s24
	s_cselect_b32 s63, s49, s25
	s_cselect_b32 s13, s13, 0x18000
	s_add_u32 s2, s2, s12
	s_addc_u32 s3, s3, 0
	s_add_u32 s62, s62, s12
	s_addc_u32 s63, s63, 0
	s_add_u32 s4, s34, s13
	s_addc_u32 s5, s35, 0
	global_load_dwordx4 v[180:183], v1, s[4:5]
	global_load_dwordx4 v[130:133], v0, s[2:3]
	global_load_dwordx4 v[184:187], v1, s[4:5] offset:64
	global_load_dwordx4 v[134:137], v0, s[2:3] offset:64
	global_load_dwordx4 v[188:191], v1, s[4:5] offset:128
	global_load_dwordx4 v[138:141], v0, s[2:3] offset:128
	global_load_dwordx4 v[192:195], v1, s[4:5] offset:192
	global_load_dwordx4 v[142:145], v0, s[2:3] offset:192
	s_waitcnt vmcnt(12)
	v_pk_fma_f32 v[62:63], v[62:63], v[196:197], v[146:147]
	v_pk_fma_f32 v[64:65], v[64:65], v[198:199], v[148:149]
	v_pk_fma_f32 v[58:59], v[58:59], v[200:201], v[154:155]
	v_pk_fma_f32 v[60:61], v[60:61], v[202:203], v[156:157]
	v_pk_fma_f32 v[54:55], v[54:55], v[208:209], v[166:167]
	v_pk_fma_f32 v[56:57], v[56:57], v[210:211], v[168:169]
	v_pk_fma_f32 v[50:51], v[50:51], v[212:213], v[176:177]
	v_pk_fma_f32 v[52:53], v[52:53], v[214:215], v[178:179]
	global_store_dwordx4 v0, v[62:65], s[64:65]
	global_store_dwordx4 v0, v[58:61], s[64:65] offset:64
	global_store_dwordx4 v0, v[54:57], s[64:65] offset:128
	global_store_dwordx4 v0, v[50:53], s[64:65] offset:192
	s_add_i32 s11, s0, 112
	s_ashr_i32 s13, s11, 11
	s_mulk_i32 s13, 0x3000
	s_and_b32 s12, s11, 0x3fff
	s_lshl_b32 s12, s12, 12
	s_cmpk_lt_i32 s11, 0x4000
	s_cselect_b32 s2, s56, s60
	s_cselect_b32 s3, s57, s61
	s_cselect_b32 s64, s48, s24
	s_cselect_b32 s65, s49, s25
	s_cselect_b32 s13, s13, 0x18000
	s_add_u32 s2, s2, s12
	s_addc_u32 s3, s3, 0
	s_add_u32 s64, s64, s12
	s_addc_u32 s65, s65, 0
	s_add_u32 s4, s34, s13
	s_addc_u32 s5, s35, 0
	global_load_dwordx4 v[196:199], v1, s[4:5]
	global_load_dwordx4 v[146:149], v0, s[2:3]
	global_load_dwordx4 v[200:203], v1, s[4:5] offset:64
	global_load_dwordx4 v[154:157], v0, s[2:3] offset:64
	global_load_dwordx4 v[208:211], v1, s[4:5] offset:128
	global_load_dwordx4 v[166:169], v0, s[2:3] offset:128
	global_load_dwordx4 v[212:215], v1, s[4:5] offset:192
	global_load_dwordx4 v[176:179], v0, s[2:3] offset:192
	s_waitcnt vmcnt(12)
	v_pk_fma_f32 v[46:47], v[46:47], v[180:181], v[130:131]
	v_pk_fma_f32 v[48:49], v[48:49], v[182:183], v[132:133]
	v_pk_fma_f32 v[42:43], v[42:43], v[184:185], v[134:135]
	v_pk_fma_f32 v[44:45], v[44:45], v[186:187], v[136:137]
	v_pk_fma_f32 v[38:39], v[38:39], v[188:189], v[138:139]
	v_pk_fma_f32 v[40:41], v[40:41], v[190:191], v[140:141]
	v_pk_fma_f32 v[34:35], v[34:35], v[192:193], v[142:143]
	v_pk_fma_f32 v[36:37], v[36:37], v[194:195], v[144:145]
	global_store_dwordx4 v0, v[46:49], s[62:63]
	global_store_dwordx4 v0, v[42:45], s[62:63] offset:64
	global_store_dwordx4 v0, v[38:41], s[62:63] offset:128
	global_store_dwordx4 v0, v[34:37], s[62:63] offset:192
	s_add_i32 s11, s0, 128
	s_ashr_i32 s13, s11, 11
	s_mulk_i32 s13, 0x3000
	s_and_b32 s12, s11, 0x3fff
	s_lshl_b32 s12, s12, 12
	s_cmpk_lt_i32 s11, 0x4000
	s_cselect_b32 s2, s56, s60
	s_cselect_b32 s3, s57, s61
	s_cselect_b32 s62, s48, s24
	s_cselect_b32 s63, s49, s25
	s_cselect_b32 s13, s13, 0x18000
	s_add_u32 s2, s2, s12
	s_addc_u32 s3, s3, 0
	s_add_u32 s62, s62, s12
	s_addc_u32 s63, s63, 0
	s_add_u32 s4, s34, s13
	s_addc_u32 s5, s35, 0
	global_load_dwordx4 v[180:183], v1, s[4:5]
	global_load_dwordx4 v[130:133], v0, s[2:3]
	global_load_dwordx4 v[184:187], v1, s[4:5] offset:64
	global_load_dwordx4 v[134:137], v0, s[2:3] offset:64
	global_load_dwordx4 v[188:191], v1, s[4:5] offset:128
	global_load_dwordx4 v[138:141], v0, s[2:3] offset:128
	global_load_dwordx4 v[192:195], v1, s[4:5] offset:192
	global_load_dwordx4 v[142:145], v0, s[2:3] offset:192
	s_waitcnt vmcnt(12)
	v_pk_fma_f32 v[30:31], v[30:31], v[196:197], v[146:147]
	v_pk_fma_f32 v[32:33], v[32:33], v[198:199], v[148:149]
	v_pk_fma_f32 v[26:27], v[26:27], v[200:201], v[154:155]
	v_pk_fma_f32 v[28:29], v[28:29], v[202:203], v[156:157]
	v_pk_fma_f32 v[22:23], v[22:23], v[208:209], v[166:167]
	v_pk_fma_f32 v[24:25], v[24:25], v[210:211], v[168:169]
	v_pk_fma_f32 v[18:19], v[18:19], v[212:213], v[176:177]
	v_pk_fma_f32 v[20:21], v[20:21], v[214:215], v[178:179]
	global_store_dwordx4 v0, v[30:33], s[64:65]
	global_store_dwordx4 v0, v[26:29], s[64:65] offset:64
	global_store_dwordx4 v0, v[22:25], s[64:65] offset:128
	global_store_dwordx4 v0, v[18:21], s[64:65] offset:192
	s_waitcnt vmcnt(4)
	v_pk_fma_f32 v[14:15], v[14:15], v[180:181], v[130:131]
	v_pk_fma_f32 v[16:17], v[16:17], v[182:183], v[132:133]
	v_pk_fma_f32 v[10:11], v[10:11], v[184:185], v[134:135]
	v_pk_fma_f32 v[12:13], v[12:13], v[186:187], v[136:137]
	v_pk_fma_f32 v[6:7], v[6:7], v[188:189], v[138:139]
	v_pk_fma_f32 v[8:9], v[8:9], v[190:191], v[140:141]
	v_pk_fma_f32 v[2:3], v[2:3], v[192:193], v[142:143]
	v_pk_fma_f32 v[4:5], v[4:5], v[194:195], v[144:145]
	global_store_dwordx4 v0, v[14:17], s[62:63]
	global_store_dwordx4 v0, v[10:13], s[62:63] offset:64
	global_store_dwordx4 v0, v[6:9], s[62:63] offset:128
	global_store_dwordx4 v0, v[2:5], s[62:63] offset:192
	v_mov_b32_e32 v1, 0
	s_add_i32 s8, s8, s80
	v_readlane_b32 s56, v252, 7
	v_readlane_b32 s57, v252, 8
	v_readlane_b32 s58, v252, 9
	v_readlane_b32 s59, v252, 10
	v_readlane_b32 s60, v252, 11
	v_readlane_b32 s61, v252, 12
	v_readlane_b32 s62, v252, 13
	v_readlane_b32 s63, v252, 14
	v_readlane_b32 s64, v252, 15
	v_readlane_b32 s65, v252, 16
	v_readlane_b32 s66, v252, 17
	v_readlane_b32 s67, v252, 18
	v_readlane_b32 s68, v252, 19
	v_readlane_b32 s69, v252, 20
	v_readlane_b32 s70, v252, 21
	v_readlane_b32 s71, v252, 22
	v_readlane_b32 s0, v251, 42
	s_add_i32 s7, s7, s0
	v_readlane_b32 s0, v251, 44
	s_add_i32 s6, s6, s0
	s_cmpk_gt_i32 s8, 0x1ff
	s_cbranch_scc1 .LBB0_754

	.amdhsa_kernel _Z11mega_kernel6Paramsiii
		.amdhsa_group_segment_fixed_size 0
		.amdhsa_private_segment_fixed_size 0
		.amdhsa_kernarg_size 464
		.amdhsa_user_sgpr_count 2
		.amdhsa_user_sgpr_dispatch_ptr 0
		.amdhsa_user_sgpr_queue_ptr 0
		.amdhsa_user_sgpr_kernarg_segment_ptr 1
		.amdhsa_user_sgpr_dispatch_id 0
		.amdhsa_user_sgpr_kernarg_preload_length 0
		.amdhsa_user_sgpr_kernarg_preload_offset 0
		.amdhsa_user_sgpr_private_segment_size 0
		.amdhsa_uses_dynamic_stack 0
		.amdhsa_enable_private_segment 0
		.amdhsa_system_sgpr_workgroup_id_x 1
		.amdhsa_system_sgpr_workgroup_id_y 0
		.amdhsa_system_sgpr_workgroup_id_z 0
		.amdhsa_system_sgpr_workgroup_info 0
		.amdhsa_system_vgpr_workitem_id 2
		.amdhsa_next_free_vgpr 256
		.amdhsa_next_free_sgpr 102
		.amdhsa_accum_offset 256
		.amdhsa_reserve_vcc 1
		.amdhsa_float_round_mode_32 0
		.amdhsa_float_round_mode_16_64 0
		.amdhsa_float_denorm_mode_32 3
		.amdhsa_float_denorm_mode_16_64 3
		.amdhsa_dx10_clamp 1
		.amdhsa_ieee_mode 1
		.amdhsa_fp16_overflow 0
		.amdhsa_tg_split 0
		.amdhsa_exception_fp_ieee_invalid_op 0
		.amdhsa_exception_fp_denorm_src 0
		.amdhsa_exception_fp_ieee_div_zero 0
		.amdhsa_exception_fp_ieee_overflow 0
		.amdhsa_exception_fp_ieee_underflow 0
		.amdhsa_exception_fp_ieee_inexact 0
		.amdhsa_exception_int_div_zero 0
	.end_amdhsa_kernel

amdhsa.kernels:
  - .agpr_count:     0
    .args:
      - .offset:         0
        .size:           192
        .value_kind:     by_value
      - .offset:         192
        .size:           4
        .value_kind:     by_value
      - .offset:         196
        .size:           4
        .value_kind:     by_value
      - .offset:         200
        .size:           4
        .value_kind:     by_value
      - .offset:         208
        .size:           4
        .value_kind:     hidden_block_count_x
      - .offset:         212
        .size:           4
        .value_kind:     hidden_block_count_y
      - .offset:         216
        .size:           4
        .value_kind:     hidden_block_count_z
      - .offset:         220
        .size:           2
        .value_kind:     hidden_group_size_x
      - .offset:         222
        .size:           2
        .value_kind:     hidden_group_size_y
      - .offset:         224
        .size:           2
        .value_kind:     hidden_group_size_z
      - .offset:         226
        .size:           2
        .value_kind:     hidden_remainder_x
      - .offset:         228
        .size:           2
        .value_kind:     hidden_remainder_y
      - .offset:         230
        .size:           2
        .value_kind:     hidden_remainder_z
      - .offset:         248
        .size:           8
        .value_kind:     hidden_global_offset_x
      - .offset:         256
        .size:           8
        .value_kind:     hidden_global_offset_y
      - .offset:         264
        .size:           8
        .value_kind:     hidden_global_offset_z
      - .offset:         272
        .size:           2
        .value_kind:     hidden_grid_dims
      - .offset:         296
        .size:           8
        .value_kind:     hidden_multigrid_sync_arg
      - .offset:         328
        .size:           4
        .value_kind:     hidden_dynamic_lds_size
    .group_segment_fixed_size: 0
    .kernarg_segment_align: 8
    .kernarg_segment_size: 464
    .language:       OpenCL C
    .language_version:
      - 2
      - 0
    .max_flat_workgroup_size: 256
    .name:           _Z11mega_kernel6Paramsiii
    .private_segment_fixed_size: 0
    .sgpr_count:     108
    .sgpr_spill_count: 361
    .symbol:         _Z11mega_kernel6Paramsiii.kd
    .uniform_work_group_size: 1
    .uses_dynamic_stack: false
    .vgpr_count:     256
    .vgpr_spill_count: 0
    .wavefront_size: 64
